# MLP1A only: hand-written 256x256 tile with v_mfma_f32_16x16x32_f16 (MLP1B unchanged)
# baseline (speedup 1.0000x reference)
.LBB0_717:
	s_and_b64 vcc, exec, s[28:29]
	s_cbranch_vccz .LBB0_854
	s_cmp_gt_i32 s70, 3
	s_cbranch_scc0 .LBB0_741
	s_cmp_gt_i32 s70, 5
	s_mov_b64 s[28:29], -1
	s_cbranch_scc0 .LBB0_742
	s_cmp_gt_i32 s70, 6
	s_mov_b64 s[24:25], -1
	s_cbranch_scc0 .LBB0_832
	s_cmp_gt_i32 s70, 7
	s_cbranch_scc0 .LBB0_781
	v_readlane_b32 s24, v236, 10
	v_readlane_b32 s25, v236, 11
	s_andn2_b64 vcc, exec, s[24:25]
	s_cbranch_vccnz .LBB0_780
	s_load_dwordx2 s[28:29], s[22:23], 0x110
	s_load_dwordx2 s[24:25], s[22:23], 0x70
	v_readlane_b32 s54, v236, 21
	s_waitcnt lgkmcnt(0)
	s_add_u32 s42, s28, 0x8208000
	s_addc_u32 s43, s29, 0
	s_add_u32 s44, s28, 0x500000
	s_addc_u32 s45, s29, 0
	s_add_u32 s46, s28, 0xaa08000
	s_addc_u32 s47, s29, 0
	s_add_u32 s48, s28, 0x5000c0
	s_addc_u32 s49, s29, 0
	s_add_u32 s50, s28, 0x82080c0
	s_addc_u32 s51, s29, 0
	s_branch .LBB0_725
.LBB0_725:
	s_ashr_i32 s28, s54, 31
	s_lshr_b32 s28, s28, 28
	s_add_i32 s28, s54, s28
	s_ashr_i32 s52, s28, 4
	s_lshl_b32 s28, s52, 3
	s_or_b32 s30, s28, s83
	s_and_b64 s[28:29], s[74:75], exec
	s_cselect_b32 s28, s30, s52
	s_lshl_b32 s36, s28, 8
	s_cmp_gt_i32 s28, 39
	s_mov_b64 s[30:31], -1
	s_cbranch_scc0 .LBB0_727
	s_add_i32 s90, s36, 0xffffd800
	s_mov_b64 s[30:31], 0
	s_mov_b64 s[28:29], s[90:91]

.LBB0_729:
	s_lshl_b32 s65, s52, 4
	s_sub_i32 s65, s54, s65
	s_lshl_b32 s65, s65, 8
	s_lshl_b32 vcc_hi, s36, 11
	s_add_u32 s30, s42, vcc_hi
	s_addc_u32 s31, s43, 0
	s_lshl_b32 vcc_hi, s65, 11
	s_add_u32 s56, s44, vcc_hi
	s_addc_u32 s57, s45, 0
	s_waitcnt lgkmcnt(0)
	v_readfirstlane_b32 vcc_hi, v200
	s_lshr_b32 vcc_hi, vcc_hi, 6
	s_lshl_b32 s32, vcc_hi, 11
	s_add_u32 s32, s32, 16
	s_lshl_b32 vcc_hi, vcc_hi, 16
	s_add_u32 s30, s30, vcc_hi
	s_addc_u32 s31, s31, 0
	s_add_u32 s56, s56, vcc_hi
	s_addc_u32 s57, s57, 0
	v_bfe_u32 v173, v200, 4, 2
	v_sub_u32_e32 v173, 0, v173
	v_and_b32_e32 v173, 3, v173
	v_and_b32_e32 v172, 3, v200
	v_xor_b32_e32 v172, v172, v173
	v_bfe_u32 v173, v200, 2, 4
	v_lshlrev_b32_e32 v173, 11, v173
	v_lshl_or_b32 v170, v172, 4, v173
	v_add_u32_e32 v171, 0x8000, v170
	v_bfe_u32 v172, v200, 2, 2
	v_sub_u32_e32 v172, 0, v172
	v_and_b32_e32 v172, 3, v172
	v_bfe_u32 v173, v200, 4, 2
	v_xor_b32_e32 v172, v172, v173
	v_and_b32_e32 v173, 15, v200
	v_bfe_u32 v174, v200, 8, 1
	v_lshl_or_b32 v174, v174, 7, v173
	v_lshlrev_b32_e32 v174, 6, v174
	v_lshl_or_b32 v164, v172, 4, v174
	v_bfe_u32 v174, v200, 6, 2
	v_lshl_or_b32 v174, v174, 6, v173
	v_lshlrev_b32_e32 v174, 6, v174
	v_lshl_or_b32 v165, v172, 4, v174
	v_add_u32_e32 v165, 0x4000, v165
	v_bfe_u32 v172, v200, 6, 2
	v_bfe_u32 v173, v200, 4, 2
	v_lshlrev_b32_e32 v172, 6, v172
	v_lshl_or_b32 v172, v173, 2, v172
	v_add_u32_e32 v172, s65, v172
	v_lshlrev_b32_e32 v172, 2, v172
	global_load_dwordx4 v[132:135], v172, s[24:25]
	global_load_dwordx4 v[136:139], v172, s[24:25] offset:64
	global_load_dwordx4 v[140:143], v172, s[24:25] offset:128
	global_load_dwordx4 v[144:147], v172, s[24:25] offset:192
	s_mov_b32 s53, s32
	s_mov_b32 m0, s53
	s_nop 0
	global_load_lds_dwordx4 v170, s[30:31]
	s_add_u32 m0, s53, 0x400
	s_nop 0
	global_load_lds_dwordx4 v171, s[30:31]
	s_add_u32 m0, s53, 0x4000
	s_nop 0
	global_load_lds_dwordx4 v170, s[56:57]
	s_add_u32 m0, s53, 0x4400
	s_nop 0
	global_load_lds_dwordx4 v171, s[56:57]
	s_add_u32 s30, s30, 64
	s_addc_u32 s31, s31, 0
	s_add_u32 s56, s56, 64
	s_addc_u32 s57, s57, 0
	s_add_u32 s53, s32, 0x8000
	s_mov_b32 m0, s53
	s_nop 0
	global_load_lds_dwordx4 v170, s[30:31]
	s_add_u32 m0, s53, 0x400
	s_nop 0
	global_load_lds_dwordx4 v171, s[30:31]
	s_add_u32 m0, s53, 0x4000
	s_nop 0
	global_load_lds_dwordx4 v170, s[56:57]
	s_add_u32 m0, s53, 0x4400
	s_nop 0
	global_load_lds_dwordx4 v171, s[56:57]
	s_add_u32 s30, s30, 64
	s_addc_u32 s31, s31, 0
	s_add_u32 s56, s56, 64
	s_addc_u32 s57, s57, 0
	s_add_u32 s53, s32, 0x10000
	s_mov_b32 m0, s53
	s_nop 0
	global_load_lds_dwordx4 v170, s[30:31]
	s_add_u32 m0, s53, 0x400
	s_nop 0
	global_load_lds_dwordx4 v171, s[30:31]
	s_add_u32 m0, s53, 0x4000
	s_nop 0
	global_load_lds_dwordx4 v170, s[56:57]
	s_add_u32 m0, s53, 0x4400
	s_nop 0
	global_load_lds_dwordx4 v171, s[56:57]
	s_add_u32 s30, s30, 64
	s_addc_u32 s31, s31, 0
	s_add_u32 s56, s56, 64
	s_addc_u32 s57, s57, 0
	s_add_u32 s53, s32, 0x18000
	s_mov_b32 m0, s53
	s_nop 0
	global_load_lds_dwordx4 v170, s[30:31]
	s_add_u32 m0, s53, 0x400
	s_nop 0
	global_load_lds_dwordx4 v171, s[30:31]
	s_add_u32 m0, s53, 0x4000
	s_nop 0
	global_load_lds_dwordx4 v170, s[56:57]
	s_add_u32 m0, s53, 0x4400
	s_nop 0
	global_load_lds_dwordx4 v171, s[56:57]
	s_add_u32 s30, s30, 64
	s_addc_u32 s31, s31, 0
	s_add_u32 s56, s56, 64
	s_addc_u32 s57, s57, 0
	s_waitcnt vmcnt(12)
	s_barrier
	v_mov_b32_e32 v4, v132
	v_mov_b32_e32 v5, v133
	v_mov_b32_e32 v6, v134
	v_mov_b32_e32 v7, v135
	v_mov_b32_e32 v8, v136
	v_mov_b32_e32 v9, v137
	v_mov_b32_e32 v10, v138
	v_mov_b32_e32 v11, v139
	v_mov_b32_e32 v12, v140
	v_mov_b32_e32 v13, v141
	v_mov_b32_e32 v14, v142
	v_mov_b32_e32 v15, v143
	v_mov_b32_e32 v16, v144
	v_mov_b32_e32 v17, v145
	v_mov_b32_e32 v18, v146
	v_mov_b32_e32 v19, v147
	v_mov_b32_e32 v20, v132
	v_mov_b32_e32 v21, v133
	v_mov_b32_e32 v22, v134
	v_mov_b32_e32 v23, v135
	v_mov_b32_e32 v24, v136
	v_mov_b32_e32 v25, v137
	v_mov_b32_e32 v26, v138
	v_mov_b32_e32 v27, v139
	v_mov_b32_e32 v28, v140
	v_mov_b32_e32 v29, v141
	v_mov_b32_e32 v30, v142
	v_mov_b32_e32 v31, v143
	v_mov_b32_e32 v32, v144
	v_mov_b32_e32 v33, v145
	v_mov_b32_e32 v34, v146
	v_mov_b32_e32 v35, v147
	v_mov_b32_e32 v36, v132
	v_mov_b32_e32 v37, v133
	v_mov_b32_e32 v38, v134
	v_mov_b32_e32 v39, v135
	v_mov_b32_e32 v40, v136
	v_mov_b32_e32 v41, v137
	v_mov_b32_e32 v42, v138
	v_mov_b32_e32 v43, v139
	v_mov_b32_e32 v44, v140
	v_mov_b32_e32 v45, v141
	v_mov_b32_e32 v46, v142
	v_mov_b32_e32 v47, v143
	v_mov_b32_e32 v48, v144
	v_mov_b32_e32 v49, v145
	v_mov_b32_e32 v50, v146
	v_mov_b32_e32 v51, v147
	v_mov_b32_e32 v52, v132
	v_mov_b32_e32 v53, v133
	v_mov_b32_e32 v54, v134
	v_mov_b32_e32 v55, v135
	v_mov_b32_e32 v56, v136
	v_mov_b32_e32 v57, v137
	v_mov_b32_e32 v58, v138
	v_mov_b32_e32 v59, v139
	v_mov_b32_e32 v60, v140
	v_mov_b32_e32 v61, v141
	v_mov_b32_e32 v62, v142
	v_mov_b32_e32 v63, v143
	v_mov_b32_e32 v64, v144
	v_mov_b32_e32 v65, v145
	v_mov_b32_e32 v66, v146
	v_mov_b32_e32 v67, v147
	v_mov_b32_e32 v68, v132
	v_mov_b32_e32 v69, v133
	v_mov_b32_e32 v70, v134
	v_mov_b32_e32 v71, v135
	v_mov_b32_e32 v72, v136
	v_mov_b32_e32 v73, v137
	v_mov_b32_e32 v74, v138
	v_mov_b32_e32 v75, v139
	v_mov_b32_e32 v76, v140
	v_mov_b32_e32 v77, v141
	v_mov_b32_e32 v78, v142
	v_mov_b32_e32 v79, v143
	v_mov_b32_e32 v80, v144
	v_mov_b32_e32 v81, v145
	v_mov_b32_e32 v82, v146
	v_mov_b32_e32 v83, v147
	v_mov_b32_e32 v84, v132
	v_mov_b32_e32 v85, v133
	v_mov_b32_e32 v86, v134
	v_mov_b32_e32 v87, v135
	v_mov_b32_e32 v88, v136
	v_mov_b32_e32 v89, v137
	v_mov_b32_e32 v90, v138
	v_mov_b32_e32 v91, v139
	v_mov_b32_e32 v92, v140
	v_mov_b32_e32 v93, v141
	v_mov_b32_e32 v94, v142
	v_mov_b32_e32 v95, v143
	v_mov_b32_e32 v96, v144
	v_mov_b32_e32 v97, v145
	v_mov_b32_e32 v98, v146
	v_mov_b32_e32 v99, v147
	v_mov_b32_e32 v100, v132
	v_mov_b32_e32 v101, v133
	v_mov_b32_e32 v102, v134
	v_mov_b32_e32 v103, v135
	v_mov_b32_e32 v104, v136
	v_mov_b32_e32 v105, v137
	v_mov_b32_e32 v106, v138
	v_mov_b32_e32 v107, v139
	v_mov_b32_e32 v108, v140
	v_mov_b32_e32 v109, v141
	v_mov_b32_e32 v110, v142
	v_mov_b32_e32 v111, v143
	v_mov_b32_e32 v112, v144
	v_mov_b32_e32 v113, v145
	v_mov_b32_e32 v114, v146
	v_mov_b32_e32 v115, v147
	v_mov_b32_e32 v116, v132
	v_mov_b32_e32 v117, v133
	v_mov_b32_e32 v118, v134
	v_mov_b32_e32 v119, v135
	v_mov_b32_e32 v120, v136
	v_mov_b32_e32 v121, v137
	v_mov_b32_e32 v122, v138
	v_mov_b32_e32 v123, v139
	v_mov_b32_e32 v124, v140
	v_mov_b32_e32 v125, v141
	v_mov_b32_e32 v126, v142
	v_mov_b32_e32 v127, v143
	v_mov_b32_e32 v128, v144
	v_mov_b32_e32 v129, v145
	v_mov_b32_e32 v130, v146
	v_mov_b32_e32 v131, v147
	s_mov_b32 s37, 0
	s_mov_b32 s55, 0
	s_nop 1
	v_add_u32_e32 v168, s37, v165
	v_add_u32_e32 v169, s37, v164
	ds_read_b128 v[132:135], v168 offset:16
	ds_read_b128 v[136:139], v168 offset:1040
	ds_read_b128 v[140:143], v168 offset:2064
	ds_read_b128 v[144:147], v168 offset:3088
	ds_read_b128 v[184:187], v169 offset:16
	ds_read_b128 v[188:191], v169 offset:1040
	ds_read_b128 v[192:195], v169 offset:2064
	ds_read_b128 v[196:199], v169 offset:3088
	s_waitcnt lgkmcnt(0)
.Lt_mlp1a:
	v_add_u32_e32 v169, s37, v164
	v_mfma_f32_16x16x32_f16 v[4:7], v[132:135], v[184:187], v[4:7]
	ds_read_b128 v[238:241], v169 offset:4112
	v_mfma_f32_16x16x32_f16 v[8:11], v[136:139], v[184:187], v[8:11]
	ds_read_b128 v[242:245], v169 offset:5136
	v_mfma_f32_16x16x32_f16 v[12:15], v[140:143], v[184:187], v[12:15]
	ds_read_b128 v[246:249], v169 offset:6160
	v_mfma_f32_16x16x32_f16 v[16:19], v[144:147], v[184:187], v[16:19]
	ds_read_b128 v[250:253], v169 offset:7184
	v_mfma_f32_16x16x32_f16 v[20:23], v[132:135], v[188:191], v[20:23]
	v_mfma_f32_16x16x32_f16 v[24:27], v[136:139], v[188:191], v[24:27]
	v_mfma_f32_16x16x32_f16 v[28:31], v[140:143], v[188:191], v[28:31]
	v_mfma_f32_16x16x32_f16 v[32:35], v[144:147], v[188:191], v[32:35]
	v_mfma_f32_16x16x32_f16 v[36:39], v[132:135], v[192:195], v[36:39]
	v_mfma_f32_16x16x32_f16 v[40:43], v[136:139], v[192:195], v[40:43]
	v_mfma_f32_16x16x32_f16 v[44:47], v[140:143], v[192:195], v[44:47]
	v_mfma_f32_16x16x32_f16 v[48:51], v[144:147], v[192:195], v[48:51]
	v_mfma_f32_16x16x32_f16 v[52:55], v[132:135], v[196:199], v[52:55]
	v_mfma_f32_16x16x32_f16 v[56:59], v[136:139], v[196:199], v[56:59]
	v_mfma_f32_16x16x32_f16 v[60:63], v[140:143], v[196:199], v[60:63]
	v_mfma_f32_16x16x32_f16 v[64:67], v[144:147], v[196:199], v[64:67]
	s_waitcnt vmcnt(8) lgkmcnt(0)
	s_barrier
	s_add_i32 s53, s37, 0x8000
	s_cmp_lg_u32 s37, 0x18000
	s_cselect_b32 s53, s53, 0
	v_add_u32_e32 v168, s53, v165
	v_add_u32_e32 v169, s53, v164
	s_add_u32 vcc_lo, s32, s37
	v_mfma_f32_16x16x32_f16 v[68:71], v[132:135], v[238:241], v[68:71]
	ds_read_b128 v[148:151], v168 offset:16
	ds_read_b128 v[184:187], v169 offset:16
	v_mfma_f32_16x16x32_f16 v[72:75], v[136:139], v[238:241], v[72:75]
	ds_read_b128 v[152:155], v168 offset:1040
	ds_read_b128 v[188:191], v169 offset:1040
	v_mfma_f32_16x16x32_f16 v[76:79], v[140:143], v[238:241], v[76:79]
	ds_read_b128 v[156:159], v168 offset:2064
	ds_read_b128 v[192:195], v169 offset:2064
	v_mfma_f32_16x16x32_f16 v[80:83], v[144:147], v[238:241], v[80:83]
	ds_read_b128 v[160:163], v168 offset:3088
	ds_read_b128 v[196:199], v169 offset:3088
	v_mfma_f32_16x16x32_f16 v[84:87], v[132:135], v[242:245], v[84:87]
	v_mfma_f32_16x16x32_f16 v[88:91], v[136:139], v[242:245], v[88:91]
	v_mfma_f32_16x16x32_f16 v[92:95], v[140:143], v[242:245], v[92:95]
	v_mfma_f32_16x16x32_f16 v[96:99], v[144:147], v[242:245], v[96:99]
	v_mfma_f32_16x16x32_f16 v[100:103], v[132:135], v[246:249], v[100:103]
	s_mov_b32 m0, vcc_lo
	s_nop 0
	global_load_lds_dwordx4 v170, s[30:31]
	v_mfma_f32_16x16x32_f16 v[104:107], v[136:139], v[246:249], v[104:107]
	s_add_u32 m0, vcc_lo, 0x400
	s_nop 0
	global_load_lds_dwordx4 v171, s[30:31]
	v_mfma_f32_16x16x32_f16 v[108:111], v[140:143], v[246:249], v[108:111]
	s_add_u32 m0, vcc_lo, 0x4000
	s_nop 0
	global_load_lds_dwordx4 v170, s[56:57]
	v_mfma_f32_16x16x32_f16 v[112:115], v[144:147], v[246:249], v[112:115]
	s_add_u32 m0, vcc_lo, 0x4400
	s_nop 0
	global_load_lds_dwordx4 v171, s[56:57]
	v_mfma_f32_16x16x32_f16 v[116:119], v[132:135], v[250:253], v[116:119]
	v_mfma_f32_16x16x32_f16 v[120:123], v[136:139], v[250:253], v[120:123]
	v_mfma_f32_16x16x32_f16 v[124:127], v[140:143], v[250:253], v[124:127]
	v_mfma_f32_16x16x32_f16 v[128:131], v[144:147], v[250:253], v[128:131]
	s_waitcnt lgkmcnt(0)
	s_mov_b32 s37, s53
	s_add_u32 s30, s30, 64
	s_addc_u32 s31, s31, 0
	s_add_u32 s56, s56, 64
	s_addc_u32 s57, s57, 0
	v_add_u32_e32 v169, s37, v164
	v_mfma_f32_16x16x32_f16 v[4:7], v[148:151], v[184:187], v[4:7]
	ds_read_b128 v[238:241], v169 offset:4112
	v_mfma_f32_16x16x32_f16 v[8:11], v[152:155], v[184:187], v[8:11]
	ds_read_b128 v[242:245], v169 offset:5136
	v_mfma_f32_16x16x32_f16 v[12:15], v[156:159], v[184:187], v[12:15]
	ds_read_b128 v[246:249], v169 offset:6160
	v_mfma_f32_16x16x32_f16 v[16:19], v[160:163], v[184:187], v[16:19]
	ds_read_b128 v[250:253], v169 offset:7184
	v_mfma_f32_16x16x32_f16 v[20:23], v[148:151], v[188:191], v[20:23]
	v_mfma_f32_16x16x32_f16 v[24:27], v[152:155], v[188:191], v[24:27]
	v_mfma_f32_16x16x32_f16 v[28:31], v[156:159], v[188:191], v[28:31]
	v_mfma_f32_16x16x32_f16 v[32:35], v[160:163], v[188:191], v[32:35]
	v_mfma_f32_16x16x32_f16 v[36:39], v[148:151], v[192:195], v[36:39]
	v_mfma_f32_16x16x32_f16 v[40:43], v[152:155], v[192:195], v[40:43]
	v_mfma_f32_16x16x32_f16 v[44:47], v[156:159], v[192:195], v[44:47]
	v_mfma_f32_16x16x32_f16 v[48:51], v[160:163], v[192:195], v[48:51]
	v_mfma_f32_16x16x32_f16 v[52:55], v[148:151], v[196:199], v[52:55]
	v_mfma_f32_16x16x32_f16 v[56:59], v[152:155], v[196:199], v[56:59]
	v_mfma_f32_16x16x32_f16 v[60:63], v[156:159], v[196:199], v[60:63]
	v_mfma_f32_16x16x32_f16 v[64:67], v[160:163], v[196:199], v[64:67]
	s_waitcnt vmcnt(8) lgkmcnt(0)
	s_barrier
	s_add_i32 s53, s37, 0x8000
	s_cmp_lg_u32 s37, 0x18000
	s_cselect_b32 s53, s53, 0
	v_add_u32_e32 v168, s53, v165
	v_add_u32_e32 v169, s53, v164
	s_add_u32 vcc_lo, s32, s37
	v_mfma_f32_16x16x32_f16 v[68:71], v[148:151], v[238:241], v[68:71]
	ds_read_b128 v[132:135], v168 offset:16
	ds_read_b128 v[184:187], v169 offset:16
	v_mfma_f32_16x16x32_f16 v[72:75], v[152:155], v[238:241], v[72:75]
	ds_read_b128 v[136:139], v168 offset:1040
	ds_read_b128 v[188:191], v169 offset:1040
	v_mfma_f32_16x16x32_f16 v[76:79], v[156:159], v[238:241], v[76:79]
	ds_read_b128 v[140:143], v168 offset:2064
	ds_read_b128 v[192:195], v169 offset:2064
	v_mfma_f32_16x16x32_f16 v[80:83], v[160:163], v[238:241], v[80:83]
	ds_read_b128 v[144:147], v168 offset:3088
	ds_read_b128 v[196:199], v169 offset:3088
	v_mfma_f32_16x16x32_f16 v[84:87], v[148:151], v[242:245], v[84:87]
	v_mfma_f32_16x16x32_f16 v[88:91], v[152:155], v[242:245], v[88:91]
	v_mfma_f32_16x16x32_f16 v[92:95], v[156:159], v[242:245], v[92:95]
	v_mfma_f32_16x16x32_f16 v[96:99], v[160:163], v[242:245], v[96:99]
	v_mfma_f32_16x16x32_f16 v[100:103], v[148:151], v[246:249], v[100:103]
	s_mov_b32 m0, vcc_lo
	s_nop 0
	global_load_lds_dwordx4 v170, s[30:31]
	v_mfma_f32_16x16x32_f16 v[104:107], v[152:155], v[246:249], v[104:107]
	s_add_u32 m0, vcc_lo, 0x400
	s_nop 0
	global_load_lds_dwordx4 v171, s[30:31]
	v_mfma_f32_16x16x32_f16 v[108:111], v[156:159], v[246:249], v[108:111]
	s_add_u32 m0, vcc_lo, 0x4000
	s_nop 0
	global_load_lds_dwordx4 v170, s[56:57]
	v_mfma_f32_16x16x32_f16 v[112:115], v[160:163], v[246:249], v[112:115]
	s_add_u32 m0, vcc_lo, 0x4400
	s_nop 0
	global_load_lds_dwordx4 v171, s[56:57]
	v_mfma_f32_16x16x32_f16 v[116:119], v[148:151], v[250:253], v[116:119]
	v_mfma_f32_16x16x32_f16 v[120:123], v[152:155], v[250:253], v[120:123]
	v_mfma_f32_16x16x32_f16 v[124:127], v[156:159], v[250:253], v[124:127]
	v_mfma_f32_16x16x32_f16 v[128:131], v[160:163], v[250:253], v[128:131]
	s_waitcnt lgkmcnt(0)
	s_mov_b32 s37, s53
	s_add_u32 s30, s30, 64
	s_addc_u32 s31, s31, 0
	s_add_u32 s56, s56, 64
	s_addc_u32 s57, s57, 0
	s_add_i32 s55, s55, 2
	s_cmp_lt_u32 s55, 28
	s_cbranch_scc1 .Lt_mlp1a
	v_add_u32_e32 v169, s37, v164
	v_mfma_f32_16x16x32_f16 v[4:7], v[132:135], v[184:187], v[4:7]
	ds_read_b128 v[238:241], v169 offset:4112
	v_mfma_f32_16x16x32_f16 v[8:11], v[136:139], v[184:187], v[8:11]
	ds_read_b128 v[242:245], v169 offset:5136
	v_mfma_f32_16x16x32_f16 v[12:15], v[140:143], v[184:187], v[12:15]
	ds_read_b128 v[246:249], v169 offset:6160
	v_mfma_f32_16x16x32_f16 v[16:19], v[144:147], v[184:187], v[16:19]
	ds_read_b128 v[250:253], v169 offset:7184
	v_mfma_f32_16x16x32_f16 v[20:23], v[132:135], v[188:191], v[20:23]
	v_mfma_f32_16x16x32_f16 v[24:27], v[136:139], v[188:191], v[24:27]
	v_mfma_f32_16x16x32_f16 v[28:31], v[140:143], v[188:191], v[28:31]
	v_mfma_f32_16x16x32_f16 v[32:35], v[144:147], v[188:191], v[32:35]
	v_mfma_f32_16x16x32_f16 v[36:39], v[132:135], v[192:195], v[36:39]
	v_mfma_f32_16x16x32_f16 v[40:43], v[136:139], v[192:195], v[40:43]
	v_mfma_f32_16x16x32_f16 v[44:47], v[140:143], v[192:195], v[44:47]
	v_mfma_f32_16x16x32_f16 v[48:51], v[144:147], v[192:195], v[48:51]
	v_mfma_f32_16x16x32_f16 v[52:55], v[132:135], v[196:199], v[52:55]
	v_mfma_f32_16x16x32_f16 v[56:59], v[136:139], v[196:199], v[56:59]
	v_mfma_f32_16x16x32_f16 v[60:63], v[140:143], v[196:199], v[60:63]
	v_mfma_f32_16x16x32_f16 v[64:67], v[144:147], v[196:199], v[64:67]
	s_waitcnt vmcnt(8) lgkmcnt(0)
	s_barrier
	s_add_i32 s53, s37, 0x8000
	s_cmp_lg_u32 s37, 0x18000
	s_cselect_b32 s53, s53, 0
	v_add_u32_e32 v168, s53, v165
	v_add_u32_e32 v169, s53, v164
	v_mfma_f32_16x16x32_f16 v[68:71], v[132:135], v[238:241], v[68:71]
	ds_read_b128 v[148:151], v168 offset:16
	ds_read_b128 v[184:187], v169 offset:16
	v_mfma_f32_16x16x32_f16 v[72:75], v[136:139], v[238:241], v[72:75]
	ds_read_b128 v[152:155], v168 offset:1040
	ds_read_b128 v[188:191], v169 offset:1040
	v_mfma_f32_16x16x32_f16 v[76:79], v[140:143], v[238:241], v[76:79]
	ds_read_b128 v[156:159], v168 offset:2064
	ds_read_b128 v[192:195], v169 offset:2064
	v_mfma_f32_16x16x32_f16 v[80:83], v[144:147], v[238:241], v[80:83]
	ds_read_b128 v[160:163], v168 offset:3088
	ds_read_b128 v[196:199], v169 offset:3088
	v_mfma_f32_16x16x32_f16 v[84:87], v[132:135], v[242:245], v[84:87]
	v_mfma_f32_16x16x32_f16 v[88:91], v[136:139], v[242:245], v[88:91]
	v_mfma_f32_16x16x32_f16 v[92:95], v[140:143], v[242:245], v[92:95]
	v_mfma_f32_16x16x32_f16 v[96:99], v[144:147], v[242:245], v[96:99]
	v_mfma_f32_16x16x32_f16 v[100:103], v[132:135], v[246:249], v[100:103]
	v_mfma_f32_16x16x32_f16 v[104:107], v[136:139], v[246:249], v[104:107]
	v_mfma_f32_16x16x32_f16 v[108:111], v[140:143], v[246:249], v[108:111]
	v_mfma_f32_16x16x32_f16 v[112:115], v[144:147], v[246:249], v[112:115]
	v_mfma_f32_16x16x32_f16 v[116:119], v[132:135], v[250:253], v[116:119]
	v_mfma_f32_16x16x32_f16 v[120:123], v[136:139], v[250:253], v[120:123]
	v_mfma_f32_16x16x32_f16 v[124:127], v[140:143], v[250:253], v[124:127]
	v_mfma_f32_16x16x32_f16 v[128:131], v[144:147], v[250:253], v[128:131]
	s_waitcnt lgkmcnt(0)
	s_mov_b32 s37, s53
	v_add_u32_e32 v169, s37, v164
	v_mfma_f32_16x16x32_f16 v[4:7], v[148:151], v[184:187], v[4:7]
	ds_read_b128 v[238:241], v169 offset:4112
	v_mfma_f32_16x16x32_f16 v[8:11], v[152:155], v[184:187], v[8:11]
	ds_read_b128 v[242:245], v169 offset:5136
	v_mfma_f32_16x16x32_f16 v[12:15], v[156:159], v[184:187], v[12:15]
	ds_read_b128 v[246:249], v169 offset:6160
	v_mfma_f32_16x16x32_f16 v[16:19], v[160:163], v[184:187], v[16:19]
	ds_read_b128 v[250:253], v169 offset:7184
	v_mfma_f32_16x16x32_f16 v[20:23], v[148:151], v[188:191], v[20:23]
	v_mfma_f32_16x16x32_f16 v[24:27], v[152:155], v[188:191], v[24:27]
	v_mfma_f32_16x16x32_f16 v[28:31], v[156:159], v[188:191], v[28:31]
	v_mfma_f32_16x16x32_f16 v[32:35], v[160:163], v[188:191], v[32:35]
	v_mfma_f32_16x16x32_f16 v[36:39], v[148:151], v[192:195], v[36:39]
	v_mfma_f32_16x16x32_f16 v[40:43], v[152:155], v[192:195], v[40:43]
	v_mfma_f32_16x16x32_f16 v[44:47], v[156:159], v[192:195], v[44:47]
	v_mfma_f32_16x16x32_f16 v[48:51], v[160:163], v[192:195], v[48:51]
	v_mfma_f32_16x16x32_f16 v[52:55], v[148:151], v[196:199], v[52:55]
	v_mfma_f32_16x16x32_f16 v[56:59], v[152:155], v[196:199], v[56:59]
	v_mfma_f32_16x16x32_f16 v[60:63], v[156:159], v[196:199], v[60:63]
	v_mfma_f32_16x16x32_f16 v[64:67], v[160:163], v[196:199], v[64:67]
	s_waitcnt vmcnt(4) lgkmcnt(0)
	s_barrier
	s_add_i32 s53, s37, 0x8000
	s_cmp_lg_u32 s37, 0x18000
	s_cselect_b32 s53, s53, 0
	v_add_u32_e32 v168, s53, v165
	v_add_u32_e32 v169, s53, v164
	v_mfma_f32_16x16x32_f16 v[68:71], v[148:151], v[238:241], v[68:71]
	ds_read_b128 v[132:135], v168 offset:16
	ds_read_b128 v[184:187], v169 offset:16
	v_mfma_f32_16x16x32_f16 v[72:75], v[152:155], v[238:241], v[72:75]
	ds_read_b128 v[136:139], v168 offset:1040
	ds_read_b128 v[188:191], v169 offset:1040
	v_mfma_f32_16x16x32_f16 v[76:79], v[156:159], v[238:241], v[76:79]
	ds_read_b128 v[140:143], v168 offset:2064
	ds_read_b128 v[192:195], v169 offset:2064
	v_mfma_f32_16x16x32_f16 v[80:83], v[160:163], v[238:241], v[80:83]
	ds_read_b128 v[144:147], v168 offset:3088
	ds_read_b128 v[196:199], v169 offset:3088
	v_mfma_f32_16x16x32_f16 v[84:87], v[148:151], v[242:245], v[84:87]
	v_mfma_f32_16x16x32_f16 v[88:91], v[152:155], v[242:245], v[88:91]
	v_mfma_f32_16x16x32_f16 v[92:95], v[156:159], v[242:245], v[92:95]
	v_mfma_f32_16x16x32_f16 v[96:99], v[160:163], v[242:245], v[96:99]
	v_mfma_f32_16x16x32_f16 v[100:103], v[148:151], v[246:249], v[100:103]
	v_mfma_f32_16x16x32_f16 v[104:107], v[152:155], v[246:249], v[104:107]
	v_mfma_f32_16x16x32_f16 v[108:111], v[156:159], v[246:249], v[108:111]
	v_mfma_f32_16x16x32_f16 v[112:115], v[160:163], v[246:249], v[112:115]
	v_mfma_f32_16x16x32_f16 v[116:119], v[148:151], v[250:253], v[116:119]
	v_mfma_f32_16x16x32_f16 v[120:123], v[152:155], v[250:253], v[120:123]
	v_mfma_f32_16x16x32_f16 v[124:127], v[156:159], v[250:253], v[124:127]
	v_mfma_f32_16x16x32_f16 v[128:131], v[160:163], v[250:253], v[128:131]
	s_waitcnt lgkmcnt(0)
	s_mov_b32 s37, s53
	v_add_u32_e32 v169, s37, v164
	v_mfma_f32_16x16x32_f16 v[4:7], v[132:135], v[184:187], v[4:7]
	ds_read_b128 v[238:241], v169 offset:4112
	v_mfma_f32_16x16x32_f16 v[8:11], v[136:139], v[184:187], v[8:11]
	ds_read_b128 v[242:245], v169 offset:5136
	v_mfma_f32_16x16x32_f16 v[12:15], v[140:143], v[184:187], v[12:15]
	ds_read_b128 v[246:249], v169 offset:6160
	v_mfma_f32_16x16x32_f16 v[16:19], v[144:147], v[184:187], v[16:19]
	ds_read_b128 v[250:253], v169 offset:7184
	v_mfma_f32_16x16x32_f16 v[20:23], v[132:135], v[188:191], v[20:23]
	v_mfma_f32_16x16x32_f16 v[24:27], v[136:139], v[188:191], v[24:27]
	v_mfma_f32_16x16x32_f16 v[28:31], v[140:143], v[188:191], v[28:31]
	v_mfma_f32_16x16x32_f16 v[32:35], v[144:147], v[188:191], v[32:35]
	v_mfma_f32_16x16x32_f16 v[36:39], v[132:135], v[192:195], v[36:39]
	v_mfma_f32_16x16x32_f16 v[40:43], v[136:139], v[192:195], v[40:43]
	v_mfma_f32_16x16x32_f16 v[44:47], v[140:143], v[192:195], v[44:47]
	v_mfma_f32_16x16x32_f16 v[48:51], v[144:147], v[192:195], v[48:51]
	v_mfma_f32_16x16x32_f16 v[52:55], v[132:135], v[196:199], v[52:55]
	v_mfma_f32_16x16x32_f16 v[56:59], v[136:139], v[196:199], v[56:59]
	v_mfma_f32_16x16x32_f16 v[60:63], v[140:143], v[196:199], v[60:63]
	v_mfma_f32_16x16x32_f16 v[64:67], v[144:147], v[196:199], v[64:67]
	s_waitcnt vmcnt(0) lgkmcnt(0)
	s_barrier
	s_add_i32 s53, s37, 0x8000
	s_cmp_lg_u32 s37, 0x18000
	s_cselect_b32 s53, s53, 0
	v_add_u32_e32 v168, s53, v165
	v_add_u32_e32 v169, s53, v164
	v_mfma_f32_16x16x32_f16 v[68:71], v[132:135], v[238:241], v[68:71]
	ds_read_b128 v[148:151], v168 offset:16
	ds_read_b128 v[184:187], v169 offset:16
	v_mfma_f32_16x16x32_f16 v[72:75], v[136:139], v[238:241], v[72:75]
	ds_read_b128 v[152:155], v168 offset:1040
	ds_read_b128 v[188:191], v169 offset:1040
	v_mfma_f32_16x16x32_f16 v[76:79], v[140:143], v[238:241], v[76:79]
	ds_read_b128 v[156:159], v168 offset:2064
	ds_read_b128 v[192:195], v169 offset:2064
	v_mfma_f32_16x16x32_f16 v[80:83], v[144:147], v[238:241], v[80:83]
	ds_read_b128 v[160:163], v168 offset:3088
	ds_read_b128 v[196:199], v169 offset:3088
	v_mfma_f32_16x16x32_f16 v[84:87], v[132:135], v[242:245], v[84:87]
	v_mfma_f32_16x16x32_f16 v[88:91], v[136:139], v[242:245], v[88:91]
	v_mfma_f32_16x16x32_f16 v[92:95], v[140:143], v[242:245], v[92:95]
	v_mfma_f32_16x16x32_f16 v[96:99], v[144:147], v[242:245], v[96:99]
	v_mfma_f32_16x16x32_f16 v[100:103], v[132:135], v[246:249], v[100:103]
	v_mfma_f32_16x16x32_f16 v[104:107], v[136:139], v[246:249], v[104:107]
	v_mfma_f32_16x16x32_f16 v[108:111], v[140:143], v[246:249], v[108:111]
	v_mfma_f32_16x16x32_f16 v[112:115], v[144:147], v[246:249], v[112:115]
	v_mfma_f32_16x16x32_f16 v[116:119], v[132:135], v[250:253], v[116:119]
	v_mfma_f32_16x16x32_f16 v[120:123], v[136:139], v[250:253], v[120:123]
	v_mfma_f32_16x16x32_f16 v[124:127], v[140:143], v[250:253], v[124:127]
	v_mfma_f32_16x16x32_f16 v[128:131], v[144:147], v[250:253], v[128:131]
	s_waitcnt lgkmcnt(0)
	s_mov_b32 s37, s53
	v_add_u32_e32 v169, s37, v164
	v_mfma_f32_16x16x32_f16 v[4:7], v[148:151], v[184:187], v[4:7]
	ds_read_b128 v[238:241], v169 offset:4112
	v_mfma_f32_16x16x32_f16 v[8:11], v[152:155], v[184:187], v[8:11]
	ds_read_b128 v[242:245], v169 offset:5136
	v_mfma_f32_16x16x32_f16 v[12:15], v[156:159], v[184:187], v[12:15]
	ds_read_b128 v[246:249], v169 offset:6160
	v_mfma_f32_16x16x32_f16 v[16:19], v[160:163], v[184:187], v[16:19]
	ds_read_b128 v[250:253], v169 offset:7184
	v_mfma_f32_16x16x32_f16 v[20:23], v[148:151], v[188:191], v[20:23]
	v_mfma_f32_16x16x32_f16 v[24:27], v[152:155], v[188:191], v[24:27]
	v_mfma_f32_16x16x32_f16 v[28:31], v[156:159], v[188:191], v[28:31]
	v_mfma_f32_16x16x32_f16 v[32:35], v[160:163], v[188:191], v[32:35]
	v_mfma_f32_16x16x32_f16 v[36:39], v[148:151], v[192:195], v[36:39]
	v_mfma_f32_16x16x32_f16 v[40:43], v[152:155], v[192:195], v[40:43]
	v_mfma_f32_16x16x32_f16 v[44:47], v[156:159], v[192:195], v[44:47]
	v_mfma_f32_16x16x32_f16 v[48:51], v[160:163], v[192:195], v[48:51]
	v_mfma_f32_16x16x32_f16 v[52:55], v[148:151], v[196:199], v[52:55]
	v_mfma_f32_16x16x32_f16 v[56:59], v[152:155], v[196:199], v[56:59]
	v_mfma_f32_16x16x32_f16 v[60:63], v[156:159], v[196:199], v[60:63]
	v_mfma_f32_16x16x32_f16 v[64:67], v[160:163], v[196:199], v[64:67]
	s_waitcnt lgkmcnt(0)
	s_barrier
	v_mfma_f32_16x16x32_f16 v[68:71], v[148:151], v[238:241], v[68:71]
	v_mfma_f32_16x16x32_f16 v[72:75], v[152:155], v[238:241], v[72:75]
	v_mfma_f32_16x16x32_f16 v[76:79], v[156:159], v[238:241], v[76:79]
	v_mfma_f32_16x16x32_f16 v[80:83], v[160:163], v[238:241], v[80:83]
	v_mfma_f32_16x16x32_f16 v[84:87], v[148:151], v[242:245], v[84:87]
	v_mfma_f32_16x16x32_f16 v[88:91], v[152:155], v[242:245], v[88:91]
	v_mfma_f32_16x16x32_f16 v[92:95], v[156:159], v[242:245], v[92:95]
	v_mfma_f32_16x16x32_f16 v[96:99], v[160:163], v[242:245], v[96:99]
	v_mfma_f32_16x16x32_f16 v[100:103], v[148:151], v[246:249], v[100:103]
	v_mfma_f32_16x16x32_f16 v[104:107], v[152:155], v[246:249], v[104:107]
	v_mfma_f32_16x16x32_f16 v[108:111], v[156:159], v[246:249], v[108:111]
	v_mfma_f32_16x16x32_f16 v[112:115], v[160:163], v[246:249], v[112:115]
	v_mfma_f32_16x16x32_f16 v[116:119], v[148:151], v[250:253], v[116:119]
	v_mfma_f32_16x16x32_f16 v[120:123], v[152:155], v[250:253], v[120:123]
	v_mfma_f32_16x16x32_f16 v[124:127], v[156:159], v[250:253], v[124:127]
	v_mfma_f32_16x16x32_f16 v[128:131], v[160:163], v[250:253], v[128:131]
	s_lshl_b64 s[80:81], s[28:29], 13
	s_add_u32 s80, s80, s34
	s_addc_u32 s81, s81, s35
	s_lshl_b32 s82, s65, 1
	s_add_u32 s80, s80, s82
	s_addc_u32 s81, s81, 0
	v_and_b32_e32 v172, 15, v200
	v_bfe_u32 v173, v200, 4, 2
	v_bfe_u32 v174, v200, 6, 2
	v_bfe_u32 v175, v200, 8, 1
	v_lshl_or_b32 v175, v175, 7, v172
	v_lshlrev_b32_e32 v175, 13, v175
	v_lshlrev_b32_e32 v174, 6, v174
	v_lshl_or_b32 v174, v173, 2, v174
	v_lshl_add_u32 v177, v174, 1, v175
	v_max_f32_e32 v4, 0, v4
	v_max_f32_e32 v5, 0, v5
	v_max_f32_e32 v6, 0, v6
	v_max_f32_e32 v7, 0, v7
	v_pk_mul_f32 v[4:5], v[4:5], v[4:5]
	v_pk_mul_f32 v[6:7], v[6:7], v[6:7]
	v_cvt_pk_f16_f32 v172, v4, v5
	v_cvt_pk_f16_f32 v173, v6, v7
	global_store_dwordx2 v177, v[172:173], s[80:81]
	v_max_f32_e32 v8, 0, v8
	v_max_f32_e32 v9, 0, v9
	v_max_f32_e32 v10, 0, v10
	v_max_f32_e32 v11, 0, v11
	v_pk_mul_f32 v[8:9], v[8:9], v[8:9]
	v_pk_mul_f32 v[10:11], v[10:11], v[10:11]
	v_cvt_pk_f16_f32 v174, v8, v9
	v_cvt_pk_f16_f32 v175, v10, v11
	global_store_dwordx2 v177, v[174:175], s[80:81] offset:32
	v_max_f32_e32 v12, 0, v12
	v_max_f32_e32 v13, 0, v13
	v_max_f32_e32 v14, 0, v14
	v_max_f32_e32 v15, 0, v15
	v_pk_mul_f32 v[12:13], v[12:13], v[12:13]
	v_pk_mul_f32 v[14:15], v[14:15], v[14:15]
	v_cvt_pk_f16_f32 v172, v12, v13
	v_cvt_pk_f16_f32 v173, v14, v15
	global_store_dwordx2 v177, v[172:173], s[80:81] offset:64
	v_max_f32_e32 v16, 0, v16
	v_max_f32_e32 v17, 0, v17
	v_max_f32_e32 v18, 0, v18
	v_max_f32_e32 v19, 0, v19
	v_pk_mul_f32 v[16:17], v[16:17], v[16:17]
	v_pk_mul_f32 v[18:19], v[18:19], v[18:19]
	v_cvt_pk_f16_f32 v174, v16, v17
	v_cvt_pk_f16_f32 v175, v18, v19
	global_store_dwordx2 v177, v[174:175], s[80:81] offset:96
	v_add_u32_e32 v177, 0x20000, v177
	v_max_f32_e32 v20, 0, v20
	v_max_f32_e32 v21, 0, v21
	v_max_f32_e32 v22, 0, v22
	v_max_f32_e32 v23, 0, v23
	v_pk_mul_f32 v[20:21], v[20:21], v[20:21]
	v_pk_mul_f32 v[22:23], v[22:23], v[22:23]
	v_cvt_pk_f16_f32 v172, v20, v21
	v_cvt_pk_f16_f32 v173, v22, v23
	global_store_dwordx2 v177, v[172:173], s[80:81]
	v_max_f32_e32 v24, 0, v24
	v_max_f32_e32 v25, 0, v25
	v_max_f32_e32 v26, 0, v26
	v_max_f32_e32 v27, 0, v27
	v_pk_mul_f32 v[24:25], v[24:25], v[24:25]
	v_pk_mul_f32 v[26:27], v[26:27], v[26:27]
	v_cvt_pk_f16_f32 v174, v24, v25
	v_cvt_pk_f16_f32 v175, v26, v27
	global_store_dwordx2 v177, v[174:175], s[80:81] offset:32
	v_max_f32_e32 v28, 0, v28
	v_max_f32_e32 v29, 0, v29
	v_max_f32_e32 v30, 0, v30
	v_max_f32_e32 v31, 0, v31
	v_pk_mul_f32 v[28:29], v[28:29], v[28:29]
	v_pk_mul_f32 v[30:31], v[30:31], v[30:31]
	v_cvt_pk_f16_f32 v172, v28, v29
	v_cvt_pk_f16_f32 v173, v30, v31
	global_store_dwordx2 v177, v[172:173], s[80:81] offset:64
	v_max_f32_e32 v32, 0, v32
	v_max_f32_e32 v33, 0, v33
	v_max_f32_e32 v34, 0, v34
	v_max_f32_e32 v35, 0, v35
	v_pk_mul_f32 v[32:33], v[32:33], v[32:33]
	v_pk_mul_f32 v[34:35], v[34:35], v[34:35]
	v_cvt_pk_f16_f32 v174, v32, v33
	v_cvt_pk_f16_f32 v175, v34, v35
	global_store_dwordx2 v177, v[174:175], s[80:81] offset:96
	v_add_u32_e32 v177, 0x20000, v177
	v_max_f32_e32 v36, 0, v36
	v_max_f32_e32 v37, 0, v37
	v_max_f32_e32 v38, 0, v38
	v_max_f32_e32 v39, 0, v39
	v_pk_mul_f32 v[36:37], v[36:37], v[36:37]
	v_pk_mul_f32 v[38:39], v[38:39], v[38:39]
	v_cvt_pk_f16_f32 v172, v36, v37
	v_cvt_pk_f16_f32 v173, v38, v39
	global_store_dwordx2 v177, v[172:173], s[80:81]
	v_max_f32_e32 v40, 0, v40
	v_max_f32_e32 v41, 0, v41
	v_max_f32_e32 v42, 0, v42
	v_max_f32_e32 v43, 0, v43
	v_pk_mul_f32 v[40:41], v[40:41], v[40:41]
	v_pk_mul_f32 v[42:43], v[42:43], v[42:43]
	v_cvt_pk_f16_f32 v174, v40, v41
	v_cvt_pk_f16_f32 v175, v42, v43
	global_store_dwordx2 v177, v[174:175], s[80:81] offset:32
	v_max_f32_e32 v44, 0, v44
	v_max_f32_e32 v45, 0, v45
	v_max_f32_e32 v46, 0, v46
	v_max_f32_e32 v47, 0, v47
	v_pk_mul_f32 v[44:45], v[44:45], v[44:45]
	v_pk_mul_f32 v[46:47], v[46:47], v[46:47]
	v_cvt_pk_f16_f32 v172, v44, v45
	v_cvt_pk_f16_f32 v173, v46, v47
	global_store_dwordx2 v177, v[172:173], s[80:81] offset:64
	v_max_f32_e32 v48, 0, v48
	v_max_f32_e32 v49, 0, v49
	v_max_f32_e32 v50, 0, v50
	v_max_f32_e32 v51, 0, v51
	v_pk_mul_f32 v[48:49], v[48:49], v[48:49]
	v_pk_mul_f32 v[50:51], v[50:51], v[50:51]
	v_cvt_pk_f16_f32 v174, v48, v49
	v_cvt_pk_f16_f32 v175, v50, v51
	global_store_dwordx2 v177, v[174:175], s[80:81] offset:96
	v_add_u32_e32 v177, 0x20000, v177
	v_max_f32_e32 v52, 0, v52
	v_max_f32_e32 v53, 0, v53
	v_max_f32_e32 v54, 0, v54
	v_max_f32_e32 v55, 0, v55
	v_pk_mul_f32 v[52:53], v[52:53], v[52:53]
	v_pk_mul_f32 v[54:55], v[54:55], v[54:55]
	v_cvt_pk_f16_f32 v172, v52, v53
	v_cvt_pk_f16_f32 v173, v54, v55
	global_store_dwordx2 v177, v[172:173], s[80:81]
	v_max_f32_e32 v56, 0, v56
	v_max_f32_e32 v57, 0, v57
	v_max_f32_e32 v58, 0, v58
	v_max_f32_e32 v59, 0, v59
	v_pk_mul_f32 v[56:57], v[56:57], v[56:57]
	v_pk_mul_f32 v[58:59], v[58:59], v[58:59]
	v_cvt_pk_f16_f32 v174, v56, v57
	v_cvt_pk_f16_f32 v175, v58, v59
	global_store_dwordx2 v177, v[174:175], s[80:81] offset:32
	v_max_f32_e32 v60, 0, v60
	v_max_f32_e32 v61, 0, v61
	v_max_f32_e32 v62, 0, v62
	v_max_f32_e32 v63, 0, v63
	v_pk_mul_f32 v[60:61], v[60:61], v[60:61]
	v_pk_mul_f32 v[62:63], v[62:63], v[62:63]
	v_cvt_pk_f16_f32 v172, v60, v61
	v_cvt_pk_f16_f32 v173, v62, v63
	global_store_dwordx2 v177, v[172:173], s[80:81] offset:64
	v_max_f32_e32 v64, 0, v64
	v_max_f32_e32 v65, 0, v65
	v_max_f32_e32 v66, 0, v66
	v_max_f32_e32 v67, 0, v67
	v_pk_mul_f32 v[64:65], v[64:65], v[64:65]
	v_pk_mul_f32 v[66:67], v[66:67], v[66:67]
	v_cvt_pk_f16_f32 v174, v64, v65
	v_cvt_pk_f16_f32 v175, v66, v67
	global_store_dwordx2 v177, v[174:175], s[80:81] offset:96
	v_add_u32_e32 v177, 0x20000, v177
	v_max_f32_e32 v68, 0, v68
	v_max_f32_e32 v69, 0, v69
	v_max_f32_e32 v70, 0, v70
	v_max_f32_e32 v71, 0, v71
	v_pk_mul_f32 v[68:69], v[68:69], v[68:69]
	v_pk_mul_f32 v[70:71], v[70:71], v[70:71]
	v_cvt_pk_f16_f32 v172, v68, v69
	v_cvt_pk_f16_f32 v173, v70, v71
	global_store_dwordx2 v177, v[172:173], s[80:81]
	v_max_f32_e32 v72, 0, v72
	v_max_f32_e32 v73, 0, v73
	v_max_f32_e32 v74, 0, v74
	v_max_f32_e32 v75, 0, v75
	v_pk_mul_f32 v[72:73], v[72:73], v[72:73]
	v_pk_mul_f32 v[74:75], v[74:75], v[74:75]
	v_cvt_pk_f16_f32 v174, v72, v73
	v_cvt_pk_f16_f32 v175, v74, v75
	global_store_dwordx2 v177, v[174:175], s[80:81] offset:32
	v_max_f32_e32 v76, 0, v76
	v_max_f32_e32 v77, 0, v77
	v_max_f32_e32 v78, 0, v78
	v_max_f32_e32 v79, 0, v79
	v_pk_mul_f32 v[76:77], v[76:77], v[76:77]
	v_pk_mul_f32 v[78:79], v[78:79], v[78:79]
	v_cvt_pk_f16_f32 v172, v76, v77
	v_cvt_pk_f16_f32 v173, v78, v79
	global_store_dwordx2 v177, v[172:173], s[80:81] offset:64
	v_max_f32_e32 v80, 0, v80
	v_max_f32_e32 v81, 0, v81
	v_max_f32_e32 v82, 0, v82
	v_max_f32_e32 v83, 0, v83
	v_pk_mul_f32 v[80:81], v[80:81], v[80:81]
	v_pk_mul_f32 v[82:83], v[82:83], v[82:83]
	v_cvt_pk_f16_f32 v174, v80, v81
	v_cvt_pk_f16_f32 v175, v82, v83
	global_store_dwordx2 v177, v[174:175], s[80:81] offset:96
	v_add_u32_e32 v177, 0x20000, v177
	v_max_f32_e32 v84, 0, v84
	v_max_f32_e32 v85, 0, v85
	v_max_f32_e32 v86, 0, v86
	v_max_f32_e32 v87, 0, v87
	v_pk_mul_f32 v[84:85], v[84:85], v[84:85]
	v_pk_mul_f32 v[86:87], v[86:87], v[86:87]
	v_cvt_pk_f16_f32 v172, v84, v85
	v_cvt_pk_f16_f32 v173, v86, v87
	global_store_dwordx2 v177, v[172:173], s[80:81]
	v_max_f32_e32 v88, 0, v88
	v_max_f32_e32 v89, 0, v89
	v_max_f32_e32 v90, 0, v90
	v_max_f32_e32 v91, 0, v91
	v_pk_mul_f32 v[88:89], v[88:89], v[88:89]
	v_pk_mul_f32 v[90:91], v[90:91], v[90:91]
	v_cvt_pk_f16_f32 v174, v88, v89
	v_cvt_pk_f16_f32 v175, v90, v91
	global_store_dwordx2 v177, v[174:175], s[80:81] offset:32
	v_max_f32_e32 v92, 0, v92
	v_max_f32_e32 v93, 0, v93
	v_max_f32_e32 v94, 0, v94
	v_max_f32_e32 v95, 0, v95
	v_pk_mul_f32 v[92:93], v[92:93], v[92:93]
	v_pk_mul_f32 v[94:95], v[94:95], v[94:95]
	v_cvt_pk_f16_f32 v172, v92, v93
	v_cvt_pk_f16_f32 v173, v94, v95
	global_store_dwordx2 v177, v[172:173], s[80:81] offset:64
	v_max_f32_e32 v96, 0, v96
	v_max_f32_e32 v97, 0, v97
	v_max_f32_e32 v98, 0, v98
	v_max_f32_e32 v99, 0, v99
	v_pk_mul_f32 v[96:97], v[96:97], v[96:97]
	v_pk_mul_f32 v[98:99], v[98:99], v[98:99]
	v_cvt_pk_f16_f32 v174, v96, v97
	v_cvt_pk_f16_f32 v175, v98, v99
	global_store_dwordx2 v177, v[174:175], s[80:81] offset:96
	v_add_u32_e32 v177, 0x20000, v177
	v_max_f32_e32 v100, 0, v100
	v_max_f32_e32 v101, 0, v101
	v_max_f32_e32 v102, 0, v102
	v_max_f32_e32 v103, 0, v103
	v_pk_mul_f32 v[100:101], v[100:101], v[100:101]
	v_pk_mul_f32 v[102:103], v[102:103], v[102:103]
	v_cvt_pk_f16_f32 v172, v100, v101
	v_cvt_pk_f16_f32 v173, v102, v103
	global_store_dwordx2 v177, v[172:173], s[80:81]
	v_max_f32_e32 v104, 0, v104
	v_max_f32_e32 v105, 0, v105
	v_max_f32_e32 v106, 0, v106
	v_max_f32_e32 v107, 0, v107
	v_pk_mul_f32 v[104:105], v[104:105], v[104:105]
	v_pk_mul_f32 v[106:107], v[106:107], v[106:107]
	v_cvt_pk_f16_f32 v174, v104, v105
	v_cvt_pk_f16_f32 v175, v106, v107
	global_store_dwordx2 v177, v[174:175], s[80:81] offset:32
	v_max_f32_e32 v108, 0, v108
	v_max_f32_e32 v109, 0, v109
	v_max_f32_e32 v110, 0, v110
	v_max_f32_e32 v111, 0, v111
	v_pk_mul_f32 v[108:109], v[108:109], v[108:109]
	v_pk_mul_f32 v[110:111], v[110:111], v[110:111]
	v_cvt_pk_f16_f32 v172, v108, v109
	v_cvt_pk_f16_f32 v173, v110, v111
	global_store_dwordx2 v177, v[172:173], s[80:81] offset:64
	v_max_f32_e32 v112, 0, v112
	v_max_f32_e32 v113, 0, v113
	v_max_f32_e32 v114, 0, v114
	v_max_f32_e32 v115, 0, v115
	v_pk_mul_f32 v[112:113], v[112:113], v[112:113]
	v_pk_mul_f32 v[114:115], v[114:115], v[114:115]
	v_cvt_pk_f16_f32 v174, v112, v113
	v_cvt_pk_f16_f32 v175, v114, v115
	global_store_dwordx2 v177, v[174:175], s[80:81] offset:96
	v_add_u32_e32 v177, 0x20000, v177
	v_max_f32_e32 v116, 0, v116
	v_max_f32_e32 v117, 0, v117
	v_max_f32_e32 v118, 0, v118
	v_max_f32_e32 v119, 0, v119
	v_pk_mul_f32 v[116:117], v[116:117], v[116:117]
	v_pk_mul_f32 v[118:119], v[118:119], v[118:119]
	v_cvt_pk_f16_f32 v172, v116, v117
	v_cvt_pk_f16_f32 v173, v118, v119
	global_store_dwordx2 v177, v[172:173], s[80:81]
	v_max_f32_e32 v120, 0, v120
	v_max_f32_e32 v121, 0, v121
	v_max_f32_e32 v122, 0, v122
	v_max_f32_e32 v123, 0, v123
	v_pk_mul_f32 v[120:121], v[120:121], v[120:121]
	v_pk_mul_f32 v[122:123], v[122:123], v[122:123]
	v_cvt_pk_f16_f32 v174, v120, v121
	v_cvt_pk_f16_f32 v175, v122, v123
	global_store_dwordx2 v177, v[174:175], s[80:81] offset:32
	v_max_f32_e32 v124, 0, v124
	v_max_f32_e32 v125, 0, v125
	v_max_f32_e32 v126, 0, v126
	v_max_f32_e32 v127, 0, v127
	v_pk_mul_f32 v[124:125], v[124:125], v[124:125]
	v_pk_mul_f32 v[126:127], v[126:127], v[126:127]
	v_cvt_pk_f16_f32 v172, v124, v125
	v_cvt_pk_f16_f32 v173, v126, v127
	global_store_dwordx2 v177, v[172:173], s[80:81] offset:64
	v_max_f32_e32 v128, 0, v128
	v_max_f32_e32 v129, 0, v129
	v_max_f32_e32 v130, 0, v130
	v_max_f32_e32 v131, 0, v131
	v_pk_mul_f32 v[128:129], v[128:129], v[128:129]
	v_pk_mul_f32 v[130:131], v[130:131], v[130:131]
	v_cvt_pk_f16_f32 v174, v128, v129
	v_cvt_pk_f16_f32 v175, v130, v131
	global_store_dwordx2 v177, v[174:175], s[80:81] offset:96
	s_nop 1
	s_add_i32 s54, s54, s76
	s_cmp_ge_i32 s54, s58
	s_cbranch_scc1 .LBB0_780
	s_branch .LBB0_725

	.amdhsa_kernel _Z2mk6Params
		.amdhsa_group_segment_fixed_size 16
		.amdhsa_private_segment_fixed_size 0
		.amdhsa_kernarg_size 544
		.amdhsa_user_sgpr_count 2
		.amdhsa_user_sgpr_dispatch_ptr 0
		.amdhsa_user_sgpr_queue_ptr 0
		.amdhsa_user_sgpr_kernarg_segment_ptr 1
		.amdhsa_user_sgpr_dispatch_id 0
		.amdhsa_user_sgpr_kernarg_preload_length 0
		.amdhsa_user_sgpr_kernarg_preload_offset 0
		.amdhsa_user_sgpr_private_segment_size 0
		.amdhsa_uses_dynamic_stack 0
		.amdhsa_enable_private_segment 0
		.amdhsa_system_sgpr_workgroup_id_x 1
		.amdhsa_system_sgpr_workgroup_id_y 0
		.amdhsa_system_sgpr_workgroup_id_z 0
		.amdhsa_system_sgpr_workgroup_info 0
		.amdhsa_system_vgpr_workitem_id 2
		.amdhsa_next_free_vgpr 256
		.amdhsa_next_free_sgpr 100
		.amdhsa_accum_offset 256
		.amdhsa_reserve_vcc 1
		.amdhsa_float_round_mode_32 0
		.amdhsa_float_round_mode_16_64 0
		.amdhsa_float_denorm_mode_32 3
		.amdhsa_float_denorm_mode_16_64 3
		.amdhsa_dx10_clamp 1
		.amdhsa_ieee_mode 1
		.amdhsa_fp16_overflow 0
		.amdhsa_tg_split 0
		.amdhsa_exception_fp_ieee_invalid_op 0
		.amdhsa_exception_fp_denorm_src 0
		.amdhsa_exception_fp_ieee_div_zero 0
		.amdhsa_exception_fp_ieee_overflow 0
		.amdhsa_exception_fp_ieee_underflow 0
		.amdhsa_exception_fp_ieee_inexact 0
		.amdhsa_exception_int_div_zero 0
	.end_amdhsa_kernel

amdhsa.kernels:
  - .agpr_count:     0
    .args:
      - .offset:         0
        .size:           288
        .value_kind:     by_value
      - .offset:         288
        .size:           4
        .value_kind:     hidden_block_count_x
      - .offset:         292
        .size:           4
        .value_kind:     hidden_block_count_y
      - .offset:         296
        .size:           4
        .value_kind:     hidden_block_count_z
      - .offset:         300
        .size:           2
        .value_kind:     hidden_group_size_x
      - .offset:         302
        .size:           2
        .value_kind:     hidden_group_size_y
      - .offset:         304
        .size:           2
        .value_kind:     hidden_group_size_z
      - .offset:         306
        .size:           2
        .value_kind:     hidden_remainder_x
      - .offset:         308
        .size:           2
        .value_kind:     hidden_remainder_y
      - .offset:         310
        .size:           2
        .value_kind:     hidden_remainder_z
      - .offset:         328
        .size:           8
        .value_kind:     hidden_global_offset_x
      - .offset:         336
        .size:           8
        .value_kind:     hidden_global_offset_y
      - .offset:         344
        .size:           8
        .value_kind:     hidden_global_offset_z
      - .offset:         352
        .size:           2
        .value_kind:     hidden_grid_dims
      - .offset:         376
        .size:           8
        .value_kind:     hidden_multigrid_sync_arg
      - .offset:         408
        .size:           4
        .value_kind:     hidden_dynamic_lds_size
    .group_segment_fixed_size: 16
    .kernarg_segment_align: 8
    .kernarg_segment_size: 544
    .language:       OpenCL C
    .language_version:
      - 2
      - 0
    .max_flat_workgroup_size: 512
    .name:           _Z2mk6Params
    .private_segment_fixed_size: 0
    .sgpr_count:     106
    .sgpr_spill_count: 149
    .symbol:         _Z2mk6Params.kd
    .uniform_work_group_size: 1
    .uses_dynamic_stack: false
    .vgpr_count:     256
    .vgpr_spill_count: 0
    .wavefront_size: 64
